# v45 with barrier spin cap raised to 0x400000 polls (never reached in a legitimate run)
# speedup vs baseline: 1.0003x; 1.0003x over previous
; DI void gbar(unsigned* ctr, unsigned& gen, unsigned G) {
;     ...
;     if (threadIdx.x == 0) {
;         __builtin_amdgcn_fence(__ATOMIC_RELEASE, "agent");
;         asm volatile("s_waitcnt vmcnt(0)" ::: "memory");
;         __hip_atomic_fetch_add(ctr, 1u, __ATOMIC_RELAXED, __HIP_MEMORY_SCOPE_AGENT);
;         while (__hip_atomic_load(ctr, __ATOMIC_RELAXED, __HIP_MEMORY_SCOPE_AGENT) < gen * G) __builtin_amdgcn_s_sleep(32);
;         __builtin_amdgcn_fence(__ATOMIC_ACQUIRE, "agent");
;         asm volatile("s_waitcnt vmcnt(0)" ::: "memory");
;     }
.Lxb_wt_0:
.Lxb_nl_0:
	s_sleep 1
	global_load_dword v4, v2, s[12:13] offset:128 sc1
	s_add_u32 s0, s0, 1
	s_waitcnt vmcnt(0)
	v_cmp_ge_u32_e32 vcc, v4, v7
	s_cbranch_vccnz .Lxb_na_0
	s_cmp_lt_u32 s0, 0x400000
	s_cbranch_scc1 .Lxb_nl_0
